# attn_normrope: 64-lane wave sums via permlane32/16 swap + DPP (same butterfly order) instead of 6 ds_bpermute hops
# speedup vs baseline: 1.0198x; 1.0058x over previous
; DI bf16_t f2bf(float f) { return (bf16_t)(cvt_pk_bf16(f, f) & 0xffffu); }
; DI float wave_sum(float v) {
; #pragma unroll
;     for (int o = 32; o >= 1; o >>= 1) v += __shfl_xor(v, o, 64);
;     return v;
; }
; DI void attn_normrope_phase(const Args& a, int j) {
;     ...
;         for (int k = 0; k < NRK; ++k) { if (row0 + k * stride < TT) {
; #pragma unroll
;             for (int hh = 0; hh < 2; ++hh) {
;                 const float ss = wave_sum(x1[k][hh] * x1[k][hh] + x2[k][hh] * x2[k][hh]);
;                 const float rinv = rsqrtf(ss * (1.f / 128.f) + 1e-6f);
;                 const float y1 = x1[k][hh] * rinv * ks1, y2 = x2[k][hh] * rinv * ks2;
;                 kp[k][hh * 128 + e1] = f2bf(y1 * cs[k] - y2 * sn[k]); kp[k][hh * 128 + e2] = f2bf(y1 * sn[k] + y2 * cs[k]);
;             } } }
.LBB0_762:
	s_or_b64 exec, exec, s[8:9]
	s_waitcnt vmcnt(10)
	v_lshlrev_b32_e32 v43, 16, v31
	v_lshlrev_b32_e32 v42, 16, v19
	v_pk_mul_f32 v[44:45], v[42:43], v[42:43]
	v_lshlrev_b64 v[10:11], 9, v[10:11]
	v_add_f32_e32 v44, v44, v45
	v_lshl_add_u64 v[10:11], v[8:9], 0, v[10:11]
	s_waitcnt vmcnt(8)
	v_lshlrev_b32_e32 v19, 16, v32
	v_lshlrev_b32_e32 v18, 16, v30
	global_load_ushort v31, v[10:11], off
	global_load_ushort v33, v[10:11], off offset:64
	global_load_ushort v30, v[10:11], off offset:256
	global_load_ushort v32, v[10:11], off offset:320
	v_mov_b32_e32 v45, v44
	s_nop 1
	v_permlane32_swap_b32_e32 v44, v45
	v_add_f32_e32 v44, v44, v45
	v_mov_b32_e32 v45, v44
	s_nop 1
	v_permlane16_swap_b32_e32 v44, v45
	v_add_f32_e32 v44, v44, v45
	s_nop 1
	v_add_f32_dpp v44, v44, v44 row_ror:8 row_mask:0xf bank_mask:0xf
	s_nop 1
	v_add_f32_dpp v44, v44, v44 row_ror:4 row_mask:0xf bank_mask:0xf
	s_nop 1
	v_add_f32_dpp v44, v44, v44 quad_perm:[2,3,0,1] row_mask:0xf bank_mask:0xf
	s_nop 1
	v_add_f32_dpp v44, v44, v44 quad_perm:[1,0,3,2] row_mask:0xf bank_mask:0xf
	v_fmamk_f32 v44, v44, 0x3c000000, v183
	v_cmp_gt_f32_e64 s[8:9], s94, v44
	v_mul_f32_e32 v45, 0x4b800000, v44
	s_nop 0
	v_cndmask_b32_e64 v44, v44, v45, s[8:9]
	v_rsq_f32_e32 v44, v44
	s_nop 0
	v_mul_f32_e32 v45, 0x45800000, v44
	v_cndmask_b32_e64 v44, v44, v45, s[8:9]
	v_mul_f32_e32 v43, v44, v43
	v_mul_f32_e32 v42, v44, v42
	v_mul_f32_e32 v43, v22, v43
	v_mul_f32_e32 v42, v21, v42
	v_mul_f32_e32 v44, v0, v43
	v_fma_f32 v44, v6, v42, -v44
	v_mul_f32_e32 v43, v6, v43
	v_cvt_pk_bf16_f32 v44, v44, v44
	global_store_short v[16:17], v44, off
	v_fmac_f32_e32 v43, v0, v42
	v_cvt_pk_bf16_f32 v42, v43, v43
	global_store_short v[16:17], v42, off offset:64
	v_pk_mul_f32 v[42:43], v[18:19], v[18:19]
	s_nop 0
	v_add_f32_e32 v42, v42, v43
	v_mov_b32_e32 v43, v42
	s_nop 1
	v_permlane32_swap_b32_e32 v42, v43
	v_add_f32_e32 v42, v42, v43
	v_mov_b32_e32 v43, v42
	s_nop 1
	v_permlane16_swap_b32_e32 v42, v43
	v_add_f32_e32 v42, v42, v43
	s_nop 1
	v_add_f32_dpp v42, v42, v42 row_ror:8 row_mask:0xf bank_mask:0xf
	s_nop 1
	v_add_f32_dpp v42, v42, v42 row_ror:4 row_mask:0xf bank_mask:0xf
	s_nop 1
	v_add_f32_dpp v42, v42, v42 quad_perm:[2,3,0,1] row_mask:0xf bank_mask:0xf
	s_nop 1
	v_add_f32_dpp v42, v42, v42 quad_perm:[1,0,3,2] row_mask:0xf bank_mask:0xf
	v_fmamk_f32 v42, v42, 0x3c000000, v183
	v_cmp_gt_f32_e64 s[8:9], s94, v42
	v_mul_f32_e32 v43, 0x4b800000, v42
	s_nop 0
	v_cndmask_b32_e64 v42, v42, v43, s[8:9]
	v_rsq_f32_e32 v42, v42
	s_nop 0
	v_mul_f32_e32 v43, 0x45800000, v42
	v_cndmask_b32_e64 v42, v42, v43, s[8:9]
	v_mul_f32_e32 v19, v42, v19
	v_mul_f32_e32 v18, v42, v18
	v_mul_f32_e32 v19, v22, v19
	v_mul_f32_e32 v18, v21, v18
	v_mul_f32_e32 v42, v0, v19
	v_fma_f32 v42, v6, v18, -v42
	v_mul_f32_e32 v6, v6, v19
	v_cvt_pk_bf16_f32 v42, v42, v42
	global_store_short v[16:17], v42, off offset:256
	v_fmac_f32_e32 v6, v0, v18
	v_cvt_pk_bf16_f32 v0, v6, v6
	global_store_short v[16:17], v0, off offset:320
	s_and_saveexec_b64 s[8:9], s[6:7]
	s_cbranch_execnz .LBB0_765
	s_or_b64 exec, exec, s[8:9]
	s_and_saveexec_b64 s[6:7], s[4:5]
	s_cbranch_execnz .LBB0_766

; DI bf16_t f2bf(float f) { return (bf16_t)(cvt_pk_bf16(f, f) & 0xffffu); }
; DI float wave_sum(float v) {
; #pragma unroll
;     for (int o = 32; o >= 1; o >>= 1) v += __shfl_xor(v, o, 64);
;     return v;
; }
; DI void attn_normrope_phase(const Args& a, int j) {
;     ...
;         for (int k = 0; k < NRK; ++k) { if (row0 + k * stride < TT) {
; #pragma unroll
;             for (int hh = 0; hh < 2; ++hh) {
;                 const float ss = wave_sum(x1[k][hh] * x1[k][hh] + x2[k][hh] * x2[k][hh]);
;                 const float rinv = rsqrtf(ss * (1.f / 128.f) + 1e-6f);
;                 const float y1 = x1[k][hh] * rinv * ks1, y2 = x2[k][hh] * rinv * ks2;
;                 kp[k][hh * 128 + e1] = f2bf(y1 * cs[k] - y2 * sn[k]); kp[k][hh * 128 + e2] = f2bf(y1 * sn[k] + y2 * cs[k]);
;             } } }
.LBB0_765:
	s_waitcnt vmcnt(14)
	v_lshlrev_b32_e32 v19, 16, v41
	v_lshlrev_b32_e32 v18, 16, v39
	s_waitcnt vmcnt(13)
	v_lshlrev_b32_e32 v16, 16, v38
	v_pk_mul_f32 v[38:39], v[18:19], v[18:19]
	s_waitcnt vmcnt(12)
	v_lshlrev_b32_e32 v17, 16, v40
	v_add_f32_e32 v0, v38, v39
	v_mov_b32_e32 v6, v0
	s_nop 1
	v_permlane32_swap_b32_e32 v0, v6
	v_add_f32_e32 v0, v0, v6
	v_mov_b32_e32 v6, v0
	s_nop 1
	v_permlane16_swap_b32_e32 v0, v6
	v_add_f32_e32 v0, v0, v6
	s_nop 1
	v_add_f32_dpp v0, v0, v0 row_ror:8 row_mask:0xf bank_mask:0xf
	s_nop 1
	v_add_f32_dpp v0, v0, v0 row_ror:4 row_mask:0xf bank_mask:0xf
	s_nop 1
	v_add_f32_dpp v0, v0, v0 quad_perm:[2,3,0,1] row_mask:0xf bank_mask:0xf
	s_nop 1
	v_add_f32_dpp v0, v0, v0 quad_perm:[1,0,3,2] row_mask:0xf bank_mask:0xf
	v_fmamk_f32 v0, v0, 0x3c000000, v183
	v_cmp_gt_f32_e64 s[6:7], s94, v0
	v_mul_f32_e32 v6, 0x4b800000, v0
	s_nop 0
	v_cndmask_b32_e64 v0, v0, v6, s[6:7]
	v_rsq_f32_e32 v0, v0
	s_nop 0
	v_mul_f32_e32 v6, 0x45800000, v0
	v_cndmask_b32_e64 v0, v0, v6, s[6:7]
	v_mul_f32_e32 v6, v0, v18
	v_mul_f32_e32 v0, v0, v19
	v_mul_f32_e32 v0, v22, v0
	v_mul_f32_e32 v6, v21, v6
	v_mul_f32_e32 v18, v7, v0
	v_fma_f32 v18, v1, v6, -v18
	v_mul_f32_e32 v0, v1, v0
	v_cvt_pk_bf16_f32 v18, v18, v18
	v_fmac_f32_e32 v0, v7, v6
	global_store_short v[14:15], v18, off
	v_cvt_pk_bf16_f32 v0, v0, v0
	v_pk_mul_f32 v[18:19], v[16:17], v[16:17]
	global_store_short v[14:15], v0, off offset:64
	v_add_f32_e32 v0, v18, v19
	v_mov_b32_e32 v6, v0
	s_nop 1
	v_permlane32_swap_b32_e32 v0, v6
	v_add_f32_e32 v0, v0, v6
	v_mov_b32_e32 v6, v0
	s_nop 1
	v_permlane16_swap_b32_e32 v0, v6
	v_add_f32_e32 v0, v0, v6
	s_nop 1
	v_add_f32_dpp v0, v0, v0 row_ror:8 row_mask:0xf bank_mask:0xf
	s_nop 1
	v_add_f32_dpp v0, v0, v0 row_ror:4 row_mask:0xf bank_mask:0xf
	s_nop 1
	v_add_f32_dpp v0, v0, v0 quad_perm:[2,3,0,1] row_mask:0xf bank_mask:0xf
	s_nop 1
	v_add_f32_dpp v0, v0, v0 quad_perm:[1,0,3,2] row_mask:0xf bank_mask:0xf
	v_fmamk_f32 v0, v0, 0x3c000000, v183
	v_cmp_gt_f32_e64 s[6:7], s94, v0
	v_mul_f32_e32 v6, 0x4b800000, v0
	s_nop 0
	v_cndmask_b32_e64 v0, v0, v6, s[6:7]
	v_rsq_f32_e32 v0, v0
	s_nop 0
	v_mul_f32_e32 v6, 0x45800000, v0
	v_cndmask_b32_e64 v0, v0, v6, s[6:7]
	v_mul_f32_e32 v6, v0, v16
	v_mul_f32_e32 v0, v0, v17
	v_mul_f32_e32 v0, v22, v0
	v_mul_f32_e32 v6, v21, v6
	v_mul_f32_e32 v16, v7, v0
	v_mul_f32_e32 v0, v1, v0
	v_fma_f32 v16, v1, v6, -v16
	v_fmac_f32_e32 v0, v7, v6
	v_cvt_pk_bf16_f32 v16, v16, v16
	global_store_short v[14:15], v16, off offset:256
	v_cvt_pk_bf16_f32 v0, v0, v0
	global_store_short v[14:15], v0, off offset:320
	s_or_b64 exec, exec, s[8:9]
	s_and_saveexec_b64 s[6:7], s[4:5]
	s_cbranch_execz .LBB0_764
; DI bf16_t f2bf(float f) { return (bf16_t)(cvt_pk_bf16(f, f) & 0xffffu); }
; DI float wave_sum(float v) {
; #pragma unroll
;     for (int o = 32; o >= 1; o >>= 1) v += __shfl_xor(v, o, 64);
;     return v;
; }
; DI void attn_normrope_phase(const Args& a, int j) {
;     ...
;         for (int k = 0; k < NRK; ++k) { if (row0 + k * stride < TT) {
; #pragma unroll
;             for (int hh = 0; hh < 2; ++hh) {
;                 const float ss = wave_sum(x1[k][hh] * x1[k][hh] + x2[k][hh] * x2[k][hh]);
;                 const float rinv = rsqrtf(ss * (1.f / 128.f) + 1e-6f);
;                 const float y1 = x1[k][hh] * rinv * ks1, y2 = x2[k][hh] * rinv * ks2;
;                 kp[k][hh * 128 + e1] = f2bf(y1 * cs[k] - y2 * sn[k]); kp[k][hh * 128 + e2] = f2bf(y1 * sn[k] + y2 * cs[k]);
;             } } }
.LBB0_766:
	s_waitcnt vmcnt(10)
	v_lshlrev_b32_e32 v7, 16, v37
	v_lshlrev_b32_e32 v6, 16, v35
	v_pk_mul_f32 v[14:15], v[6:7], v[6:7]
	s_waitcnt vmcnt(8)
	v_lshlrev_b32_e32 v1, 16, v36
	v_add_f32_e32 v14, v14, v15
	v_lshlrev_b32_e32 v0, 16, v34
	v_mov_b32_e32 v15, v14
	s_nop 1
	v_permlane32_swap_b32_e32 v14, v15
	v_add_f32_e32 v14, v14, v15
	v_mov_b32_e32 v15, v14
	s_nop 1
	v_permlane16_swap_b32_e32 v14, v15
	v_add_f32_e32 v14, v14, v15
	s_nop 1
	v_add_f32_dpp v14, v14, v14 row_ror:8 row_mask:0xf bank_mask:0xf
	s_nop 1
	v_add_f32_dpp v14, v14, v14 row_ror:4 row_mask:0xf bank_mask:0xf
	s_nop 1
	v_add_f32_dpp v14, v14, v14 quad_perm:[2,3,0,1] row_mask:0xf bank_mask:0xf
	s_nop 1
	v_add_f32_dpp v14, v14, v14 quad_perm:[1,0,3,2] row_mask:0xf bank_mask:0xf
	v_fmamk_f32 v14, v14, 0x3c000000, v183
	v_cmp_gt_f32_e64 s[4:5], s94, v14
	v_mul_f32_e32 v15, 0x4b800000, v14
	s_nop 0
	v_cndmask_b32_e64 v14, v14, v15, s[4:5]
	v_rsq_f32_e32 v14, v14
	s_nop 0
	v_mul_f32_e32 v15, 0x45800000, v14
	v_cndmask_b32_e64 v14, v14, v15, s[4:5]
	v_mul_f32_e32 v7, v14, v7
	v_mul_f32_e32 v6, v14, v6
	v_mul_f32_e32 v7, v22, v7
	v_mul_f32_e32 v6, v21, v6
	v_mul_f32_e32 v14, v2, v7
	v_fma_f32 v14, v4, v6, -v14
	v_mul_f32_e32 v7, v4, v7
	v_cvt_pk_bf16_f32 v14, v14, v14
	global_store_short v[12:13], v14, off
	v_fmac_f32_e32 v7, v2, v6
	v_cvt_pk_bf16_f32 v6, v7, v7
	global_store_short v[12:13], v6, off offset:64
	v_pk_mul_f32 v[6:7], v[0:1], v[0:1]
	s_nop 0
	v_add_f32_e32 v6, v6, v7
	v_mov_b32_e32 v7, v6
	s_nop 1
	v_permlane32_swap_b32_e32 v6, v7
	v_add_f32_e32 v6, v6, v7
	v_mov_b32_e32 v7, v6
	s_nop 1
	v_permlane16_swap_b32_e32 v6, v7
	v_add_f32_e32 v6, v6, v7
	s_nop 1
	v_add_f32_dpp v6, v6, v6 row_ror:8 row_mask:0xf bank_mask:0xf
	s_nop 1
	v_add_f32_dpp v6, v6, v6 row_ror:4 row_mask:0xf bank_mask:0xf
	s_nop 1
	v_add_f32_dpp v6, v6, v6 quad_perm:[2,3,0,1] row_mask:0xf bank_mask:0xf
	s_nop 1
	v_add_f32_dpp v6, v6, v6 quad_perm:[1,0,3,2] row_mask:0xf bank_mask:0xf
	v_fmamk_f32 v6, v6, 0x3c000000, v183
	v_cmp_gt_f32_e64 s[4:5], s94, v6
	v_mul_f32_e32 v7, 0x4b800000, v6
	s_nop 0
	v_cndmask_b32_e64 v6, v6, v7, s[4:5]
	v_rsq_f32_e32 v6, v6
	s_nop 0
	v_mul_f32_e32 v7, 0x45800000, v6
	v_cndmask_b32_e64 v6, v6, v7, s[4:5]
	v_mul_f32_e32 v1, v6, v1
	v_mul_f32_e32 v0, v6, v0
	v_mul_f32_e32 v1, v22, v1
	v_mul_f32_e32 v0, v21, v0
	v_mul_f32_e32 v6, v2, v1
	v_fma_f32 v6, v4, v0, -v6
	v_mul_f32_e32 v1, v4, v1
	v_cvt_pk_bf16_f32 v6, v6, v6
	global_store_short v[12:13], v6, off offset:256
	v_fmac_f32_e32 v1, v2, v0
	v_cvt_pk_bf16_f32 v0, v1, v1
	global_store_short v[12:13], v0, off offset:320
	s_or_b64 exec, exec, s[6:7]
	s_and_saveexec_b64 s[4:5], s[0:1]
	s_cbranch_execz .LBB0_745
.LBB0_767:
	s_waitcnt vmcnt(6)
	v_lshlrev_b32_e32 v7, 16, v33
	v_lshlrev_b32_e32 v6, 16, v31
	v_pk_mul_f32 v[12:13], v[6:7], v[6:7]
	s_waitcnt vmcnt(4)
	v_lshlrev_b32_e32 v1, 16, v32
	v_add_f32_e32 v2, v12, v13
	v_lshlrev_b32_e32 v0, 16, v30
	v_mov_b32_e32 v4, v2
	s_nop 1
	v_permlane32_swap_b32_e32 v2, v4
	v_add_f32_e32 v2, v2, v4
	v_mov_b32_e32 v4, v2
	s_nop 1
	v_permlane16_swap_b32_e32 v2, v4
	v_add_f32_e32 v2, v2, v4
	s_nop 1
	v_add_f32_dpp v2, v2, v2 row_ror:8 row_mask:0xf bank_mask:0xf
	s_nop 1
	v_add_f32_dpp v2, v2, v2 row_ror:4 row_mask:0xf bank_mask:0xf
	s_nop 1
	v_add_f32_dpp v2, v2, v2 quad_perm:[2,3,0,1] row_mask:0xf bank_mask:0xf
	s_nop 1
	v_add_f32_dpp v2, v2, v2 quad_perm:[1,0,3,2] row_mask:0xf bank_mask:0xf
	v_fmamk_f32 v2, v2, 0x3c000000, v183
	v_cmp_gt_f32_e64 s[0:1], s94, v2
	v_mul_f32_e32 v4, 0x4b800000, v2
	s_nop 0
	v_cndmask_b32_e64 v2, v2, v4, s[0:1]
	v_rsq_f32_e32 v2, v2
	s_nop 0
	v_mul_f32_e32 v4, 0x45800000, v2
	v_cndmask_b32_e64 v2, v2, v4, s[0:1]
	v_mul_f32_e32 v4, v2, v6
	v_mul_f32_e32 v2, v2, v7
	v_mul_f32_e32 v2, v22, v2
	v_mul_f32_e32 v4, v21, v4
	v_mul_f32_e32 v6, v5, v2
	v_fma_f32 v6, v3, v4, -v6
	v_mul_f32_e32 v2, v3, v2
	v_cvt_pk_bf16_f32 v6, v6, v6
	v_fmac_f32_e32 v2, v5, v4
	global_store_short v[10:11], v6, off
	v_cvt_pk_bf16_f32 v2, v2, v2
	v_pk_mul_f32 v[6:7], v[0:1], v[0:1]
	global_store_short v[10:11], v2, off offset:64
	v_add_f32_e32 v2, v6, v7
	v_mov_b32_e32 v4, v2
	s_nop 1
	v_permlane32_swap_b32_e32 v2, v4
	v_add_f32_e32 v2, v2, v4
	v_mov_b32_e32 v4, v2
	s_nop 1
	v_permlane16_swap_b32_e32 v2, v4
	v_add_f32_e32 v2, v2, v4
	s_nop 1
	v_add_f32_dpp v2, v2, v2 row_ror:8 row_mask:0xf bank_mask:0xf
	s_nop 1
	v_add_f32_dpp v2, v2, v2 row_ror:4 row_mask:0xf bank_mask:0xf
	s_nop 1
	v_add_f32_dpp v2, v2, v2 quad_perm:[2,3,0,1] row_mask:0xf bank_mask:0xf
	s_nop 1
	v_add_f32_dpp v2, v2, v2 quad_perm:[1,0,3,2] row_mask:0xf bank_mask:0xf
	v_fmamk_f32 v2, v2, 0x3c000000, v183
	v_cmp_gt_f32_e64 s[0:1], s94, v2
	v_mul_f32_e32 v4, 0x4b800000, v2
	s_nop 0
	v_cndmask_b32_e64 v2, v2, v4, s[0:1]
	v_rsq_f32_e32 v2, v2
	s_nop 0
	v_mul_f32_e32 v4, 0x45800000, v2
	v_cndmask_b32_e64 v2, v2, v4, s[0:1]
	v_mul_f32_e32 v1, v2, v1
	v_mul_f32_e32 v0, v2, v0
	v_mul_f32_e32 v1, v22, v1
	v_mul_f32_e32 v0, v21, v0
	v_mul_f32_e32 v2, v5, v1
	v_fma_f32 v2, v3, v0, -v2
	v_mul_f32_e32 v1, v3, v1
	v_cvt_pk_bf16_f32 v2, v2, v2
	global_store_short v[10:11], v2, off offset:256
	v_fmac_f32_e32 v1, v5, v0
	v_cvt_pk_bf16_f32 v0, v1, v1
	global_store_short v[10:11], v0, off offset:320
	s_branch .LBB0_745
